# group A: DMA issue in PV gaps, P0 cvt and V g3 prefetch at end of softmax; K fragment reads 8 MFMAs ahead
# baseline (speedup 1.0000x reference)
; #define MFMA(a, b, c) __builtin_amdgcn_mfma_f32_32x32x16_bf16((a), (b), (c), 0, 0, 0)
; #define LAS __attribute__((address_space(3)))
; #define D_BAR do { asm volatile("" ::: "memory"); __builtin_amdgcn_s_barrier(); asm volatile("" ::: "memory"); } while (0)
; DI void diff_core(unsigned char* smem, const u16* qptr, const u16* kbase, const u16* vtbase, int vld,
;                   int ntb, int ntw, int nvalid, int ks0, const float* lut, int qpos, bool active, bool grpB,
;                   f32x16 (&O)[4], float& l_out) {
;     ...
;   auto qk = [&](int slot) {
;     if (grpB) __builtin_amdgcn_s_setprio(2); else __builtin_amdgcn_s_setprio(1);
;     const float ini = -m;
; #pragma unroll
;     for (int kb = 0; kb < 2; ++kb)
; #pragma unroll
;       for (int e = 0; e < 16; ++e) S[kb][e] = ini;
;     const LAS unsigned char* b = lds + slot * D_SLOT;
;     bf16x8 kf[4][2];
; #pragma unroll
;     for (int s = 0; s < 4; ++s)
; #pragma unroll
;       for (int kb = 0; kb < 2; ++kb) kf[s][kb] = *reinterpret_cast<const LAS bf16x8*>(b + koff[s] + kb * 32 * 256);
; #pragma unroll
;     for (int s = 0; s < 4; ++s)
; #pragma unroll
;       for (int kb = 0; kb < 2; ++kb) S[kb] = MFMA(kf[s][kb], qf[s], S[kb]);
;     __builtin_amdgcn_sched_group_barrier(0x100, 8, 0);
;     __builtin_amdgcn_sched_group_barrier(0x008, 8, 0);
;     __builtin_amdgcn_s_setprio(0);
;   };
;     ...
;     for (int t = 0; t <= ntb; ++t) {
;       const bool act_t = active && (t < ntw);
;       if (active && t >= 1 && (t - 1) < ntw) pv((t + 3) & 3);
;       __builtin_amdgcn_sched_barrier(0);
;       if (act_t) qk(t & 3);
;       asm volatile("s_waitcnt vmcnt(4)" ::: "memory");
;       D_BAR;
;       { const int tn = t + 3; dma(tn < tlast ? tn : tlast, tn & 3); }
;       if (act_t) softmax(t);
.LBB0_354:
	s_lshl_b32 s16, s57, 10
	v_lshlrev_b32_e32 v184, 7, v2
	v_lshrrev_b32_e32 v2, 1, v0
	s_add_i32 s16, s16, 0
	v_bfe_u32 v0, v0, 1, 3
	v_bitop3_b32 v2, v1, v2, 7 bitop3:0x78
	s_add_i32 s64, s16, 0x20000
	s_lshr_b32 s16, s39, 1
	v_lshlrev_b32_e32 v188, 4, v2
	v_bitop3_b32 v2, v1, v0, 2 bitop3:0x36
	s_add_i32 s16, s16, s58
	v_lshlrev_b32_e32 v187, 4, v2
	v_bitop3_b32 v2, v1, v0, 4 bitop3:0x36
	v_bitop3_b32 v0, v1, v0, 6 bitop3:0x36
	v_lshlrev_b32_e32 v183, 4, v1
	v_or_b32_e32 v189, s63, v182
	v_lshlrev_b32_e32 v186, 4, v2
	v_lshlrev_b32_e32 v185, 4, v0
	s_add_i32 s17, s16, -3
	v_add_u32_e32 v190, s64, v183
	s_and_b64 vcc, exec, s[0:1]
	s_mov_b64 s[0:1], -1
	s_cbranch_vccnz .LBB0_370
	s_setprio 1
	v_add_u32_e32 v0, 0, v177
	ds_read_b128 v[32:35], v0
	ds_read_b128 v[36:39], v0 offset:8192
	v_add_u32_e32 v0, 0, v178
	s_mov_b32 s85, s84
	ds_read_b128 v[40:43], v0
	ds_read_b128 v[44:47], v0 offset:8192
	v_add_u32_e32 v0, 0, v179
	s_mov_b32 s86, s84
	s_mov_b32 s87, s84
	s_mov_b32 s88, s84
	s_mov_b32 s89, s84
	s_mov_b32 s90, s84
	s_mov_b32 s91, s84
	s_mov_b32 s92, s84
	s_mov_b32 s93, s84
	s_mov_b32 s94, s84
	s_mov_b32 s95, s84
	s_mov_b32 s96, s84
	s_mov_b32 s97, s84
	s_mov_b32 s98, s84
	s_mov_b32 s99, s84
	v_mov_b64_e32 v[16:17], s[84:85]
	ds_read_b128 v[48:51], v0
	ds_read_b128 v[52:55], v0 offset:8192
	v_add_u32_e32 v0, 0, v180
	v_mov_b64_e32 v[18:19], s[86:87]
	v_mov_b64_e32 v[20:21], s[88:89]
	v_mov_b64_e32 v[22:23], s[90:91]
	v_mov_b64_e32 v[24:25], s[92:93]
	v_mov_b64_e32 v[26:27], s[94:95]
	v_mov_b64_e32 v[28:29], s[96:97]
	v_mov_b64_e32 v[30:31], s[98:99]
	ds_read_b128 v[56:59], v0
	ds_read_b128 v[60:63], v0 offset:8192
	s_waitcnt lgkmcnt(0)
	v_mfma_f32_32x32x16_bf16 v[0:15], v[32:35], v[128:131], v[16:31]
	v_mfma_f32_32x32x16_bf16 v[16:31], v[36:39], v[128:131], v[16:31]
	v_mfma_f32_32x32x16_bf16 v[0:15], v[40:43], v[132:135], v[0:15]
	v_mfma_f32_32x32x16_bf16 v[16:31], v[44:47], v[132:135], v[16:31]
	v_mfma_f32_32x32x16_bf16 v[0:15], v[48:51], v[136:139], v[0:15]
	v_mfma_f32_32x32x16_bf16 v[16:31], v[52:55], v[136:139], v[16:31]
	v_mfma_f32_32x32x16_bf16 v[0:15], v[56:59], v[140:143], v[0:15]
	v_mfma_f32_32x32x16_bf16 v[16:31], v[60:63], v[140:143], v[16:31]
	s_setprio 0
	s_min_u32 s63, s58, 3
	s_add_i32 m0, s6, 0x18000
	s_lshl_b32 s0, s63, 17
	s_add_u32 s0, s14, s0
	s_waitcnt vmcnt(4)
	s_addc_u32 s1, s15, 0
	s_barrier
	v_lshl_add_u64 v[32:33], s[0:1], 0, v[162:163]
	s_lshl_b32 s63, s63, 7
	s_nop 0
	s_add_i32 m0, s6, 0x1a000
	v_lshl_add_u64 v[32:33], s[0:1], 0, v[170:171]
	s_add_u32 s0, s20, s63
	s_addc_u32 s1, s21, 0
	s_nop 0
	v_lshl_add_u64 v[32:33], s[0:1], 0, v[166:167]
	s_add_i32 m0, s6, 0x1c000
	s_nop 0
	s_nop 0
	v_lshl_add_u64 v[32:33], s[0:1], 0, v[168:169]
	s_add_i32 m0, s6, 0x1e000
	s_cmp_gt_u32 s16, 3
	s_nop 0
	s_cbranch_scc1 .LBB0_357
	v_lshlrev_b32_e32 v32, 2, v189
	v_sub_u32_e32 v48, v190, v32
	ds_read2_b32 v[32:33], v48 offset0:207 offset1:208
	ds_read2_b32 v[34:35], v48 offset0:209 offset1:210
	ds_read2_b32 v[36:37], v48 offset0:215 offset1:216
	ds_read2_b32 v[38:39], v48 offset0:217 offset1:218
	ds_read2_b32 v[40:41], v48 offset0:191 offset1:192
	ds_read2_b32 v[42:43], v48 offset0:193 offset1:194
	ds_read2_b32 v[44:45], v48 offset0:199 offset1:200
	ds_read2_b32 v[46:47], v48 offset0:201 offset1:202
	s_waitcnt lgkmcnt(0)
	v_pk_add_f32 v[14:15], v[14:15], v[38:39]
	v_pk_add_f32 v[12:13], v[12:13], v[36:37]
	v_pk_add_f32 v[10:11], v[10:11], v[34:35]
	v_pk_add_f32 v[8:9], v[8:9], v[32:33]
	v_pk_add_f32 v[6:7], v[6:7], v[46:47]
	v_pk_add_f32 v[4:5], v[4:5], v[44:45]
	v_pk_add_f32 v[2:3], v[2:3], v[42:43]
	v_pk_add_f32 v[0:1], v[0:1], v[40:41]
	ds_read2_b32 v[32:33], v48 offset0:239 offset1:240
	ds_read2_b32 v[34:35], v48 offset0:241 offset1:242
	ds_read2_b32 v[36:37], v48 offset0:247 offset1:248
	ds_read2_b32 v[38:39], v48 offset0:249 offset1:250
	ds_read2_b32 v[40:41], v48 offset0:223 offset1:224
	ds_read2_b32 v[42:43], v48 offset0:225 offset1:226
	ds_read2_b32 v[44:45], v48 offset0:231 offset1:232
	ds_read2_b32 v[46:47], v48 offset0:233 offset1:234
	s_waitcnt lgkmcnt(0)
	v_pk_add_f32 v[30:31], v[30:31], v[38:39]
	v_pk_add_f32 v[28:29], v[28:29], v[36:37]
	v_pk_add_f32 v[26:27], v[26:27], v[34:35]
	v_pk_add_f32 v[24:25], v[24:25], v[32:33]
	v_pk_add_f32 v[22:23], v[22:23], v[46:47]
	v_pk_add_f32 v[20:21], v[20:21], v[44:45]
	v_pk_add_f32 v[18:19], v[18:19], v[42:43]
	v_pk_add_f32 v[16:17], v[16:17], v[40:41]
; DI void diff_core(unsigned char* smem, const u16* qptr, const u16* kbase, const u16* vtbase, int vld,
;                   int ntb, int ntw, int nvalid, int ks0, const float* lut, int qpos, bool active, bool grpB,
;                   f32x16 (&O)[4], float& l_out) {
;     ...
;     float mx = S[0][0];
; #pragma unroll
;     for (int kb = 0; kb < 2; ++kb)
; #pragma unroll
;       for (int i = 0; i < 16; ++i) mx = fmaxf(mx, S[kb][i]);
;     {
;       const unsigned um = __float_as_uint(mx);
;       const auto sw = __builtin_amdgcn_permlane32_swap(um, um, false, false);
;       mx = fmaxf(__uint_as_float(sw[0]), __uint_as_float(sw[1]));
;     }
;     if (t == 0) {
;       m = mx;
; #pragma unroll
;       for (int kb = 0; kb < 2; ++kb)
; #pragma unroll
;         for (int i = 0; i < 16; ++i) S[kb][i] -= mx;
;     } else if (__any(mx > 8.f)) {
;       const float d = fmaxf(mx, 0.f);
;       const float alpha = __builtin_amdgcn_exp2f(-d);
;       m += d;
;       l *= alpha;
; #pragma unroll
;       for (int tt = 0; tt < 4; ++tt)
; #pragma unroll
;         for (int e = 0; e < 16; ++e) O[tt][e] *= alpha;
; #pragma unroll
;       for (int kb = 0; kb < 2; ++kb)
; #pragma unroll
;         for (int i = 0; i < 16; ++i) S[kb][i] -= d;
;     }
;     float ps = 0.f;
; #pragma unroll
;     for (int kb = 0; kb < 2; ++kb)
; #pragma unroll
;       for (int i = 0; i < 16; ++i) {
;         const float pe = __builtin_amdgcn_exp2f(S[kb][i]);
;         S[kb][i] = pe;
;         ps += pe;
;       }
;     l += ps;
.LBB0_357:
	v_max_f32_e32 v32, v1, v1
	v_max_f32_e32 v33, v0, v0
	v_max_f32_e32 v32, v33, v32
	v_max3_f32 v32, v32, v2, v3
	v_max3_f32 v32, v32, v4, v5
	v_max3_f32 v32, v32, v6, v7
	v_max3_f32 v32, v32, v8, v9
	v_max3_f32 v32, v32, v10, v11
	v_max3_f32 v32, v32, v12, v13
	v_max3_f32 v32, v32, v14, v15
	v_max3_f32 v32, v32, v16, v17
	v_max3_f32 v32, v32, v18, v19
	v_max3_f32 v32, v32, v20, v21
	v_max3_f32 v32, v32, v22, v23
	v_max3_f32 v32, v32, v24, v25
	v_max3_f32 v32, v32, v26, v27
	v_max3_f32 v32, v32, v28, v29
	v_max3_f32 v32, v32, v30, v31
	v_mov_b32_e32 v33, v32
	s_nop 1
	v_permlane32_swap_b32_e32 v32, v33
	v_max_f32_e32 v33, v33, v33
	v_max_f32_e32 v32, v32, v32
	v_max_f32_e32 v191, v32, v33
	v_xor_b32_e32 v232, 0x80000000, v191
	v_mov_b32_e32 v233, v232
	v_mov_b32_e32 v234, v232
	v_mov_b32_e32 v235, v232
	v_mov_b32_e32 v236, v232
	v_mov_b32_e32 v237, v232
	v_mov_b32_e32 v238, v232
	v_mov_b32_e32 v239, v232
	v_mov_b32_e32 v240, v232
	v_mov_b32_e32 v241, v232
	v_mov_b32_e32 v242, v232
	v_mov_b32_e32 v243, v232
	v_mov_b32_e32 v244, v232
	v_mov_b32_e32 v245, v232
	v_mov_b32_e32 v246, v232
	v_mov_b32_e32 v247, v232
	v_sub_f32_e32 v0, v0, v191
	v_sub_f32_e32 v1, v1, v191
	v_exp_f32_e32 v96, v0
	v_sub_f32_e32 v2, v2, v191
	v_exp_f32_e32 v97, v1
	v_sub_f32_e32 v3, v3, v191
	v_exp_f32_e32 v98, v2
	v_sub_f32_e32 v4, v4, v191
	v_exp_f32_e32 v99, v3
	v_sub_f32_e32 v5, v5, v191
	v_exp_f32_e32 v100, v4
	v_sub_f32_e32 v6, v6, v191
	v_exp_f32_e32 v101, v5
	v_sub_f32_e32 v7, v7, v191
	v_exp_f32_e32 v102, v6
	v_sub_f32_e32 v8, v8, v191
	v_exp_f32_e32 v103, v7
	v_sub_f32_e32 v9, v9, v191
	v_exp_f32_e32 v104, v8
	v_sub_f32_e32 v10, v10, v191
	v_exp_f32_e32 v105, v9
	v_sub_f32_e32 v11, v11, v191
	v_exp_f32_e32 v106, v10
	v_sub_f32_e32 v12, v12, v191
	v_exp_f32_e32 v107, v11
	v_sub_f32_e32 v13, v13, v191
	v_exp_f32_e32 v108, v12
	v_sub_f32_e32 v14, v14, v191
	v_exp_f32_e32 v109, v13
	v_sub_f32_e32 v15, v15, v191
	v_exp_f32_e32 v110, v14
	v_sub_f32_e32 v16, v16, v191
	v_exp_f32_e32 v111, v15
	v_sub_f32_e32 v17, v17, v191
	v_exp_f32_e32 v112, v16
	v_sub_f32_e32 v18, v18, v191
	v_exp_f32_e32 v113, v17
	v_sub_f32_e32 v19, v19, v191
	v_exp_f32_e32 v114, v18
	v_sub_f32_e32 v20, v20, v191
	v_exp_f32_e32 v115, v19
	v_sub_f32_e32 v21, v21, v191
	v_exp_f32_e32 v116, v20
	v_sub_f32_e32 v22, v22, v191
	v_exp_f32_e32 v117, v21
	v_sub_f32_e32 v23, v23, v191
	v_exp_f32_e32 v118, v22
	v_sub_f32_e32 v24, v24, v191
	v_exp_f32_e32 v119, v23
	v_sub_f32_e32 v25, v25, v191
	v_exp_f32_e32 v120, v24
	v_sub_f32_e32 v26, v26, v191
	v_exp_f32_e32 v121, v25
	v_sub_f32_e32 v27, v27, v191
	v_exp_f32_e32 v122, v26
	v_sub_f32_e32 v28, v28, v191
	v_exp_f32_e32 v123, v27
	v_sub_f32_e32 v29, v29, v191
	v_exp_f32_e32 v124, v28
	v_sub_f32_e32 v30, v30, v191
	v_exp_f32_e32 v125, v29
	v_sub_f32_e32 v31, v31, v191
	v_exp_f32_e32 v126, v30
	v_exp_f32_e32 v127, v31
	s_lshl_b32 s0, s62, 1
	s_sub_i32 s63, 0, s0
	s_lshl_b32 s0, s59, 10
	s_lshl_b32 s1, s62, 9
	s_add_i32 s0, s0, s1
	v_mov_b32_e32 v181, 0
	v_or_b32_e32 v0, s0, v183
	v_lshlrev_b32_e32 v1, 2, v182
	v_sub_u32_e32 v0, v0, v1
	s_lshl_b32 s0, s39, 7
	v_subrev_u32_e32 v0, s0, v0
	v_mov_b32_e32 v14, v163
	v_mov_b32_e32 v15, v163
	v_add_u32_e32 v199, s38, v0
	v_mov_b32_e32 v0, v163
	v_mov_b32_e32 v1, v163
	v_mov_b32_e32 v2, v163
	v_mov_b32_e32 v3, v163
	v_mov_b32_e32 v4, v163
	v_mov_b32_e32 v5, v163
	v_mov_b32_e32 v6, v163
	v_mov_b32_e32 v7, v163
	v_mov_b32_e32 v8, v163
	v_mov_b32_e32 v9, v163
	v_mov_b32_e32 v10, v163
	v_mov_b32_e32 v11, v163
	v_mov_b32_e32 v12, v163
	v_mov_b32_e32 v13, v163
	v_mov_b64_e32 v[30:31], v[14:15]
	v_mov_b64_e32 v[46:47], v[14:15]
	v_mov_b64_e32 v[62:63], v[14:15]
	v_add_u32_e32 v195, v188, v184
	v_add_u32_e32 v196, v187, v184
	v_add_u32_e32 v197, v186, v184
	v_add_u32_e32 v198, v185, v184
	s_movk_i32 s64, 0xff00
	s_mov_b32 s65, 0x20000
	v_mov_b64_e32 v[28:29], v[12:13]
	v_mov_b64_e32 v[26:27], v[10:11]
	v_mov_b64_e32 v[24:25], v[8:9]
	v_mov_b64_e32 v[22:23], v[6:7]
	v_mov_b64_e32 v[20:21], v[4:5]
	v_mov_b64_e32 v[18:19], v[2:3]
	v_mov_b64_e32 v[16:17], v[0:1]
	v_mov_b64_e32 v[44:45], v[12:13]
	v_mov_b64_e32 v[42:43], v[10:11]
	v_mov_b64_e32 v[40:41], v[8:9]
	v_mov_b64_e32 v[38:39], v[6:7]
	v_mov_b64_e32 v[36:37], v[4:5]
	v_mov_b64_e32 v[34:35], v[2:3]
	v_mov_b64_e32 v[32:33], v[0:1]
	v_mov_b64_e32 v[60:61], v[12:13]
	v_mov_b64_e32 v[58:59], v[10:11]
	v_mov_b64_e32 v[56:57], v[8:9]
	v_mov_b64_e32 v[54:55], v[6:7]
	v_mov_b64_e32 v[52:53], v[4:5]
	v_mov_b64_e32 v[50:51], v[2:3]
	v_mov_b64_e32 v[48:49], v[0:1]
	s_mov_b32 s0, 0
	v_add_u32_e32 v248, s0, v195
	ds_read_b128 v[200:203], v248 offset:16384
	ds_read_b128 v[204:207], v248 offset:20480
	ds_read_b128 v[208:211], v248 offset:24576
	ds_read_b128 v[212:215], v248 offset:28672
	v_add_u32_e32 v249, s0, v196
	ds_read_b128 v[216:219], v249 offset:16384
	ds_read_b128 v[220:223], v249 offset:20480
	ds_read_b128 v[224:227], v249 offset:24576
	ds_read_b128 v[228:231], v249 offset:28672
	v_add_u32_e32 v248, s0, v197
	ds_read_b128 v[64:67], v248 offset:16384
	ds_read_b128 v[68:71], v248 offset:20480
	ds_read_b128 v[72:75], v248 offset:24576
	ds_read_b128 v[76:79], v248 offset:28672
	v_cvt_pk_bf16_f32 v144, v96, v97
	v_cvt_pk_bf16_f32 v145, v98, v99
	v_cvt_pk_bf16_f32 v146, v100, v101
	v_cvt_pk_bf16_f32 v147, v102, v103
	v_add_f32_e32 v250, v97, v96
	v_add_f32_e32 v250, v98, v250
	s_branch .LBB0_360
; #define LAS __attribute__((address_space(3)))
; DI void diff_core(unsigned char* smem, const u16* qptr, const u16* kbase, const u16* vtbase, int vld,
;                   int ntb, int ntw, int nvalid, int ks0, const float* lut, int qpos, bool active, bool grpB,
;                   f32x16 (&O)[4], float& l_out) {
;     ...
;   auto dma_piece = [&](int t, int slot, int piece) {
;     LAS unsigned char* b = lds + slot * D_SLOT + w * 1024;
;     const char* kt = (const char*)kbase + (size_t)(64 * t) * kld * 2;
;     const char* vt = (const char*)vtbase + (size_t)(64 * t) * 2;
;     if (piece == 0) __builtin_amdgcn_global_load_lds((const unsigned*)(kt + ksrc[0]), (LAS unsigned*)(b), 16, 0, 0);
;     else if (piece == 1) __builtin_amdgcn_global_load_lds((const unsigned*)(kt + ksrc[1]), (LAS unsigned*)(b + 8192), 16, 0, 0);
;     else if (piece == 2) __builtin_amdgcn_global_load_lds((const unsigned*)(vt + vsrc[0]), (LAS unsigned*)(b + 16384), 16, 0, 0);
;     else __builtin_amdgcn_global_load_lds((const unsigned*)(vt + vsrc[1]), (LAS unsigned*)(b + 24576), 16, 0, 0);
;   };
;   auto dma = [&](int t, int slot) { dma_piece(t, slot, 0); dma_piece(t, slot, 1); dma_piece(t, slot, 2); dma_piece(t, slot, 3); };
;     ...
;     float ps = 0.f;
; #pragma unroll
;     for (int kb = 0; kb < 2; ++kb)
; #pragma unroll
;       for (int i = 0; i < 16; ++i) {
;         const float pe = __builtin_amdgcn_exp2f(S[kb][i]);
;         S[kb][i] = pe;
;         ps += pe;
;       }
;     l += ps;
; #pragma unroll
;     for (int kb = 0; kb < 2; ++kb)
; #pragma unroll
;       for (int s2 = 0; s2 < 2; ++s2) {
;         u32x4 pk;
;         pk.x = pack2(S[kb][8 * s2 + 0], S[kb][8 * s2 + 1]);
;         pk.y = pack2(S[kb][8 * s2 + 2], S[kb][8 * s2 + 3]);
;         pk.z = pack2(S[kb][8 * s2 + 4], S[kb][8 * s2 + 5]);
;         pk.w = pack2(S[kb][8 * s2 + 6], S[kb][8 * s2 + 7]);
;         P[kb * 2 + s2] = pk;
;       }
.LA_dma_only:
	s_mov_b32 m0, s85
	s_nop 0
	global_load_lds_dwordx4 v162, s[88:89]
	s_add_i32 m0, s85, 0x2000
	s_nop 0
	global_load_lds_dwordx4 v170, s[88:89]
	s_add_i32 m0, s85, 0x4000
	s_nop 0
	global_load_lds_dwordx4 v166, s[86:87]
	s_add_i32 m0, s85, 0x6000
	s_nop 0
	global_load_lds_dwordx4 v168, s[86:87]
	s_branch .LBB0_362
.LBB0_358:
	v_exp_f32_e32 v96, v96
	v_exp_f32_e32 v97, v97
	v_exp_f32_e32 v98, v98
	v_exp_f32_e32 v99, v99
	v_exp_f32_e32 v100, v100
	v_exp_f32_e32 v101, v101
	v_exp_f32_e32 v102, v102
	v_exp_f32_e32 v103, v103
	v_exp_f32_e32 v104, v104
	v_exp_f32_e32 v105, v105
	v_exp_f32_e32 v106, v106
	v_exp_f32_e32 v107, v107
	v_exp_f32_e32 v108, v108
	v_exp_f32_e32 v109, v109
	v_exp_f32_e32 v110, v110
	v_exp_f32_e32 v111, v111
	v_exp_f32_e32 v112, v112
	v_exp_f32_e32 v113, v113
	v_exp_f32_e32 v114, v114
	v_exp_f32_e32 v115, v115
	v_exp_f32_e32 v116, v116
	v_exp_f32_e32 v117, v117
	v_exp_f32_e32 v118, v118
	v_exp_f32_e32 v119, v119
	v_exp_f32_e32 v120, v120
	v_exp_f32_e32 v121, v121
	v_exp_f32_e32 v122, v122
	v_exp_f32_e32 v123, v123
	v_exp_f32_e32 v124, v124
	v_exp_f32_e32 v125, v125
	v_exp_f32_e32 v126, v126
	v_exp_f32_e32 v127, v127
	s_add_i32 s0, s65, 0x8000
	s_and_b32 s0, s0, 0x18000
	v_add_u32_e32 v248, s0, v195
	ds_read_b128 v[200:203], v248 offset:16384
	ds_read_b128 v[204:207], v248 offset:20480
	ds_read_b128 v[208:211], v248 offset:24576
	ds_read_b128 v[212:215], v248 offset:28672
	v_add_u32_e32 v249, s0, v196
	ds_read_b128 v[216:219], v249 offset:16384
	ds_read_b128 v[220:223], v249 offset:20480
	ds_read_b128 v[224:227], v249 offset:24576
	ds_read_b128 v[228:231], v249 offset:28672
	v_add_u32_e32 v248, s0, v197
	ds_read_b128 v[64:67], v248 offset:16384
	ds_read_b128 v[68:71], v248 offset:20480
	ds_read_b128 v[72:75], v248 offset:24576
	ds_read_b128 v[76:79], v248 offset:28672
	v_cvt_pk_bf16_f32 v144, v96, v97
	v_cvt_pk_bf16_f32 v145, v98, v99
	v_cvt_pk_bf16_f32 v146, v100, v101
	v_cvt_pk_bf16_f32 v147, v102, v103
	v_add_f32_e32 v250, v97, v96
	v_add_f32_e32 v250, v98, v250

; #define MFMA(a, b, c) __builtin_amdgcn_mfma_f32_32x32x16_bf16((a), (b), (c), 0, 0, 0)
; #define LAS __attribute__((address_space(3)))
; DI void diff_core(unsigned char* smem, const u16* qptr, const u16* kbase, const u16* vtbase, int vld,
;                   int ntb, int ntw, int nvalid, int ks0, const float* lut, int qpos, bool active, bool grpB,
;                   f32x16 (&O)[4], float& l_out) {
;     ...
;   auto pv = [&](int slot) {
;     if (grpB) __builtin_amdgcn_s_setprio(2); else __builtin_amdgcn_s_setprio(1);
;     const LAS unsigned char* b = lds + slot * D_SLOT;
;     bf16x8 va[4], vb[4];
; #pragma unroll
;     for (int tt = 0; tt < 4; ++tt) va[tt] = *reinterpret_cast<const LAS bf16x8*>(b + voff[0] + tt * 32 * 128);
; #pragma unroll
;     for (int tt = 0; tt < 4; ++tt) vb[tt] = *reinterpret_cast<const LAS bf16x8*>(b + voff[1] + tt * 32 * 128);
;     {
;       const bf16x8 pf = __builtin_bit_cast(bf16x8, P[0]);
; #pragma unroll
;       for (int tt = 0; tt < 4; ++tt) O[tt] = MFMA(va[tt], pf, O[tt]);
;     }
; #pragma unroll
;     for (int tt = 0; tt < 4; ++tt) va[tt] = *reinterpret_cast<const LAS bf16x8*>(b + voff[2] + tt * 32 * 128);
;     {
;       const bf16x8 pf = __builtin_bit_cast(bf16x8, P[1]);
; #pragma unroll
;       for (int tt = 0; tt < 4; ++tt) O[tt] = MFMA(vb[tt], pf, O[tt]);
;     }
; #pragma unroll
;     for (int tt = 0; tt < 4; ++tt) vb[tt] = *reinterpret_cast<const LAS bf16x8*>(b + voff[3] + tt * 32 * 128);
;     {
;       const bf16x8 pf = __builtin_bit_cast(bf16x8, P[2]);
; #pragma unroll
;       for (int tt = 0; tt < 4; ++tt) O[tt] = MFMA(va[tt], pf, O[tt]);
;     }
;     {
;       const bf16x8 pf = __builtin_bit_cast(bf16x8, P[3]);
; #pragma unroll
;       for (int tt = 0; tt < 4; ++tt) O[tt] = MFMA(vb[tt], pf, O[tt]);
;     }
;     __builtin_amdgcn_sched_group_barrier(0x100, 8, 0);
;     __builtin_amdgcn_sched_group_barrier(0x008, 4, 0);
;     __builtin_amdgcn_sched_group_barrier(0x100, 4, 0);
;     __builtin_amdgcn_sched_group_barrier(0x008, 4, 0);
;     __builtin_amdgcn_sched_group_barrier(0x100, 4, 0);
;     __builtin_amdgcn_sched_group_barrier(0x008, 8, 0);
;     __builtin_amdgcn_s_setprio(0);
;   };
;     ...
;       { const int tn = t + 3; dma(tn < tlast ? tn : tlast, tn & 3); }
.LBB0_360:
	s_add_i32 s66, s64, 0x101
	s_add_i32 s67, s64, 0x103
	s_min_i32 s67, s67, s58
	s_lshl_b32 s86, s67, 6
	s_add_i32 s85, s65, 0xffff8000
	s_and_b32 s85, s85, 0x18000
	s_ashr_i32 s87, s86, 31
	s_add_i32 s85, s6, s85
	s_lshl_b64 s[88:89], s[86:87], 11
	s_add_u32 s88, s14, s88
	s_addc_u32 s89, s15, s89
	s_lshl_b64 s[86:87], s[86:87], 1
	s_add_u32 s86, s20, s86
	s_addc_u32 s87, s21, s87
	s_cmp_gt_u32 s66, s16
	s_cbranch_scc1 .LA_dma_only
	s_setprio 1
	s_and_b32 s0, s65, 0x18000
	s_add_i32 s100, s65, 0xfffe8000
	s_and_b32 s100, s100, 0x18000
	s_waitcnt lgkmcnt(4)
	s_mov_b32 m0, s85
	v_mfma_f32_32x32x16_bf16 v[48:63], v[200:203], v[144:147], v[48:63]
	v_cvt_pk_bf16_f32 v148, v104, v105
	v_add_f32_e32 v250, v99, v250
	v_add_f32_e32 v250, v100, v250
	global_load_lds_dwordx4 v162, s[88:89]
	v_add_u32_e32 v249, s0, v198
	ds_read_b128 v[80:83], v249 offset:16384
	ds_read_b128 v[84:87], v249 offset:20480
	ds_read_b128 v[88:91], v249 offset:24576
	ds_read_b128 v[92:95], v249 offset:28672
	s_add_i32 m0, s85, 0x2000
	v_mfma_f32_32x32x16_bf16 v[32:47], v[204:207], v[144:147], v[32:47]
	v_cvt_pk_bf16_f32 v149, v106, v107
	v_add_f32_e32 v250, v101, v250
	v_add_f32_e32 v250, v102, v250
	global_load_lds_dwordx4 v170, s[88:89]
	s_add_i32 m0, s85, 0x4000
	v_mfma_f32_32x32x16_bf16 v[16:31], v[208:211], v[144:147], v[16:31]
	v_cvt_pk_bf16_f32 v150, v108, v109
	v_add_f32_e32 v250, v103, v250
	v_add_f32_e32 v250, v104, v250
	global_load_lds_dwordx4 v166, s[86:87]
	s_add_i32 m0, s85, 0x6000
	v_mfma_f32_32x32x16_bf16 v[0:15], v[212:215], v[144:147], v[0:15]
	v_cvt_pk_bf16_f32 v151, v110, v111
	v_add_f32_e32 v250, v105, v250
	v_add_f32_e32 v250, v106, v250
	global_load_lds_dwordx4 v168, s[86:87]
	v_mfma_f32_32x32x16_bf16 v[48:63], v[216:219], v[148:151], v[48:63]
	v_cvt_pk_bf16_f32 v152, v112, v113
	v_add_f32_e32 v250, v107, v250
	v_add_f32_e32 v250, v108, v250
	v_mfma_f32_32x32x16_bf16 v[32:47], v[220:223], v[148:151], v[32:47]
	v_cvt_pk_bf16_f32 v153, v114, v115
	v_add_f32_e32 v250, v109, v250
	v_add_f32_e32 v250, v110, v250
	v_mfma_f32_32x32x16_bf16 v[16:31], v[224:227], v[148:151], v[16:31]
	v_cvt_pk_bf16_f32 v154, v116, v117
	v_add_f32_e32 v250, v111, v250
	v_add_f32_e32 v250, v112, v250
	v_mfma_f32_32x32x16_bf16 v[0:15], v[228:231], v[148:151], v[0:15]
	v_cvt_pk_bf16_f32 v155, v118, v119
	v_add_f32_e32 v250, v113, v250
	v_add_f32_e32 v250, v114, v250
	s_waitcnt lgkmcnt(4)
	v_add_u32_e32 v248, s100, v177
	ds_read_b128 v[200:203], v248
	ds_read_b128 v[204:207], v248 offset:8192
	v_add_u32_e32 v249, s100, v178
	ds_read_b128 v[208:211], v249
	ds_read_b128 v[212:215], v249 offset:8192
	v_add_u32_e32 v248, s100, v179
	ds_read_b128 v[216:219], v248
	ds_read_b128 v[220:223], v248 offset:8192
	v_add_u32_e32 v249, s100, v180
	ds_read_b128 v[224:227], v249
	ds_read_b128 v[228:231], v249 offset:8192
	v_mfma_f32_32x32x16_bf16 v[48:63], v[64:67], v[152:155], v[48:63]
	v_cvt_pk_bf16_f32 v156, v120, v121
	v_add_f32_e32 v250, v115, v250
	v_add_f32_e32 v250, v116, v250
	v_mfma_f32_32x32x16_bf16 v[32:47], v[68:71], v[152:155], v[32:47]
	v_cvt_pk_bf16_f32 v157, v122, v123
	v_add_f32_e32 v250, v117, v250
	v_add_f32_e32 v250, v118, v250
	v_mfma_f32_32x32x16_bf16 v[16:31], v[72:75], v[152:155], v[16:31]
	v_cvt_pk_bf16_f32 v158, v124, v125
	v_add_f32_e32 v250, v119, v250
	v_add_f32_e32 v250, v120, v250
	v_mfma_f32_32x32x16_bf16 v[0:15], v[76:79], v[152:155], v[0:15]
	v_cvt_pk_bf16_f32 v159, v126, v127
	v_add_f32_e32 v250, v121, v250
	v_add_f32_e32 v250, v122, v250
	s_waitcnt lgkmcnt(8)
	v_mfma_f32_32x32x16_bf16 v[48:63], v[80:83], v[156:159], v[48:63]
	v_add_f32_e32 v250, v123, v250
	v_add_f32_e32 v250, v124, v250
	v_mfma_f32_32x32x16_bf16 v[32:47], v[84:87], v[156:159], v[32:47]
	v_add_f32_e32 v250, v125, v250
	v_add_f32_e32 v250, v126, v250
	v_mfma_f32_32x32x16_bf16 v[16:31], v[88:91], v[156:159], v[16:31]
	v_add_f32_e32 v250, v127, v250
	v_mfma_f32_32x32x16_bf16 v[0:15], v[92:95], v[156:159], v[0:15]
	v_add_f32_e32 v181, v181, v250
	s_setprio 0

; DI int crow(int i, int hh) { return (i & 3) + 8 * (i >> 2) + 4 * hh; }
; #define D_BAR do { asm volatile("" ::: "memory"); __builtin_amdgcn_s_barrier(); asm volatile("" ::: "memory"); } while (0)
; DI void diff_core(unsigned char* smem, const u16* qptr, const u16* kbase, const u16* vtbase, int vld,
;                   int ntb, int ntw, int nvalid, int ks0, const float* lut, int qpos, bool active, bool grpB,
;                   f32x16 (&O)[4], float& l_out) {
;     ...
;     if (lut != nullptr && t >= ntw - 3) {
;       const int base = t * 64 - qpos + 191;
; #pragma unroll
;       for (int kb = 0; kb < 2; ++kb)
; #pragma unroll
;         for (int i = 0; i < 16; ++i) S[kb][i] += lut[base + kb * 32 + crow(i, hh)];
;     }
;     ...
;       asm volatile("s_waitcnt vmcnt(4)" ::: "memory");
;       D_BAR;
;       { const int tn = t + 3; dma(tn < tlast ? tn : tlast, tn & 3); }
;       if (act_t) softmax(t);
.LBB0_364:
	s_waitcnt vmcnt(4)
	s_barrier
	s_andn2_b64 vcc, exec, s[0:1]
	s_cbranch_vccnz .LBB0_359
	s_cmp_lt_i32 s66, s17
	s_cbranch_scc1 .LBB0_367
	ds_read2_b32 v[144:145], v199 offset1:1
	ds_read2_b32 v[146:147], v199 offset0:16 offset1:17
	ds_read2_b32 v[148:149], v199 offset0:18 offset1:19
	ds_read2_b32 v[150:151], v199 offset0:24 offset1:25
	ds_read2_b32 v[152:153], v199 offset0:26 offset1:27
	ds_read2_b32 v[154:155], v199 offset0:2 offset1:3
	ds_read2_b32 v[156:157], v199 offset0:8 offset1:9
	ds_read2_b32 v[158:159], v199 offset0:10 offset1:11
	s_waitcnt lgkmcnt(0)
	v_pk_add_f32 v[96:97], v[96:97], v[144:145]
	v_pk_add_f32 v[110:111], v[110:111], v[152:153]
	v_pk_add_f32 v[108:109], v[108:109], v[150:151]
	v_pk_add_f32 v[106:107], v[106:107], v[148:149]
	v_pk_add_f32 v[104:105], v[104:105], v[146:147]
	v_pk_add_f32 v[102:103], v[102:103], v[158:159]
	v_pk_add_f32 v[100:101], v[100:101], v[156:157]
	v_pk_add_f32 v[98:99], v[98:99], v[154:155]
	ds_read2_b32 v[144:145], v199 offset0:32 offset1:33
	ds_read2_b32 v[146:147], v199 offset0:48 offset1:49
	ds_read2_b32 v[148:149], v199 offset0:50 offset1:51
	ds_read2_b32 v[150:151], v199 offset0:56 offset1:57
	ds_read2_b32 v[152:153], v199 offset0:58 offset1:59
	ds_read2_b32 v[154:155], v199 offset0:34 offset1:35
	ds_read2_b32 v[156:157], v199 offset0:40 offset1:41
	ds_read2_b32 v[158:159], v199 offset0:42 offset1:43
	s_waitcnt lgkmcnt(0)
	v_pk_add_f32 v[112:113], v[112:113], v[144:145]
	v_pk_add_f32 v[126:127], v[126:127], v[152:153]
	v_pk_add_f32 v[124:125], v[124:125], v[150:151]
	v_pk_add_f32 v[122:123], v[122:123], v[148:149]
	v_pk_add_f32 v[120:121], v[120:121], v[146:147]
	v_pk_add_f32 v[118:119], v[118:119], v[158:159]
	v_pk_add_f32 v[116:117], v[116:117], v[156:157]
	v_pk_add_f32 v[114:115], v[114:115], v[154:155]

; #define LAS __attribute__((address_space(3)))
; DI void diff_core(unsigned char* smem, const u16* qptr, const u16* kbase, const u16* vtbase, int vld,
;                   int ntb, int ntw, int nvalid, int ks0, const float* lut, int qpos, bool active, bool grpB,
;                   f32x16 (&O)[4], float& l_out) {
;     ...
;     for (int s = 0; s < 4; ++s)
; #pragma unroll
;       for (int kb = 0; kb < 2; ++kb) kf[s][kb] = *reinterpret_cast<const LAS bf16x8*>(b + koff[s] + kb * 32 * 256);
; #pragma unroll
;     for (int s = 0; s < 4; ++s)
; #pragma unroll
;       for (int kb = 0; kb < 2; ++kb) S[kb] = MFMA(kf[s][kb], qf[s], S[kb]);
;     ...
;   auto pv = [&](int slot) {
;     if (grpB) __builtin_amdgcn_s_setprio(2); else __builtin_amdgcn_s_setprio(1);
;     const LAS unsigned char* b = lds + slot * D_SLOT;
;     bf16x8 va[4], vb[4];
; #pragma unroll
;     for (int tt = 0; tt < 4; ++tt) va[tt] = *reinterpret_cast<const LAS bf16x8*>(b + voff[0] + tt * 32 * 128);
; #pragma unroll
;     for (int tt = 0; tt < 4; ++tt) vb[tt] = *reinterpret_cast<const LAS bf16x8*>(b + voff[1] + tt * 32 * 128);
;     {
;       const bf16x8 pf = __builtin_bit_cast(bf16x8, P[0]);
; #pragma unroll
;       for (int tt = 0; tt < 4; ++tt) O[tt] = MFMA(va[tt], pf, O[tt]);
;     }
; #pragma unroll
;     for (int tt = 0; tt < 4; ++tt) va[tt] = *reinterpret_cast<const LAS bf16x8*>(b + voff[2] + tt * 32 * 128);
;     {
;       const bf16x8 pf = __builtin_bit_cast(bf16x8, P[1]);
; #pragma unroll
;       for (int tt = 0; tt < 4; ++tt) O[tt] = MFMA(vb[tt], pf, O[tt]);
;     }
; #pragma unroll
;     for (int tt = 0; tt < 4; ++tt) vb[tt] = *reinterpret_cast<const LAS bf16x8*>(b + voff[3] + tt * 32 * 128);
;     {
;       const bf16x8 pf = __builtin_bit_cast(bf16x8, P[2]);
; #pragma unroll
;       for (int tt = 0; tt < 4; ++tt) O[tt] = MFMA(va[tt], pf, O[tt]);
;     }
;     {
;       const bf16x8 pf = __builtin_bit_cast(bf16x8, P[3]);
; #pragma unroll
;       for (int tt = 0; tt < 4; ++tt) O[tt] = MFMA(vb[tt], pf, O[tt]);
;     }
;     __builtin_amdgcn_sched_group_barrier(0x100, 8, 0);
;     __builtin_amdgcn_sched_group_barrier(0x008, 4, 0);
;     __builtin_amdgcn_sched_group_barrier(0x100, 4, 0);
;     __builtin_amdgcn_sched_group_barrier(0x008, 4, 0);
;     __builtin_amdgcn_sched_group_barrier(0x100, 4, 0);
;     __builtin_amdgcn_sched_group_barrier(0x008, 8, 0);
;     __builtin_amdgcn_s_setprio(0);
;   };
.LBB0_384:
	s_waitcnt vmcnt(4)
	s_barrier
	s_andn2_b64 vcc, exec, s[0:1]
	s_cbranch_vccnz .LB_dma_only
	s_setprio 2
	s_add_i32 s0, s59, 0xffff0000
	s_and_b32 s0, s0, 0x18000
	v_add_u32_e32 v97, s0, v186
	ds_read_b128 v[98:101], v97 offset:16384
	ds_read_b128 v[102:105], v97 offset:20480
	ds_read_b128 v[106:109], v97 offset:24576
	ds_read_b128 v[110:113], v97 offset:28672
	s_add_i32 s101, s59, 0xffff8000
	s_and_b32 s101, s101, 0x18000
	s_waitcnt lgkmcnt(4)
	s_mov_b32 m0, s85
	v_mfma_f32_32x32x16_bf16 v[48:63], v[200:203], v[144:147], v[48:63]
	v_cvt_pk_bf16_f32 v148, v88, v89
	v_add_f32_e32 v250, v83, v250
	v_add_f32_e32 v250, v84, v250
	global_load_lds_dwordx4 v162, s[86:87]
	v_add_u32_e32 v126, s0, v184
	ds_read_b128 v[114:117], v126 offset:16384
	ds_read_b128 v[118:121], v126 offset:20480
	ds_read_b128 v[122:125], v126 offset:24576
	ds_read_b128 v[196:199], v126 offset:28672
	s_mov_b32 m0, s65
	v_mfma_f32_32x32x16_bf16 v[32:47], v[204:207], v[144:147], v[32:47]
	v_cvt_pk_bf16_f32 v149, v90, v91
	v_add_f32_e32 v250, v85, v250
	v_add_f32_e32 v250, v86, v250
	global_load_lds_dwordx4 v170, s[86:87]
	s_mov_b32 m0, s88
	v_mfma_f32_32x32x16_bf16 v[16:31], v[208:211], v[144:147], v[16:31]
	v_cvt_pk_bf16_f32 v150, v92, v93
	v_add_f32_e32 v250, v87, v250
	v_add_f32_e32 v250, v88, v250
	global_load_lds_dwordx4 v166, s[66:67]
	s_mov_b32 m0, s89
	v_mfma_f32_32x32x16_bf16 v[0:15], v[212:215], v[144:147], v[0:15]
	v_cvt_pk_bf16_f32 v151, v94, v95
	v_add_f32_e32 v250, v89, v250
	v_add_f32_e32 v250, v90, v250
	global_load_lds_dwordx4 v168, s[66:67]
	v_mfma_f32_32x32x16_bf16 v[48:63], v[216:219], v[148:151], v[48:63]
	v_cvt_pk_bf16_f32 v152, v64, v65
	v_add_f32_e32 v250, v91, v250
	v_add_f32_e32 v250, v92, v250
	v_mfma_f32_32x32x16_bf16 v[32:47], v[220:223], v[148:151], v[32:47]
	v_cvt_pk_bf16_f32 v153, v66, v67
	v_add_f32_e32 v250, v93, v250
	v_add_f32_e32 v250, v94, v250
	v_mfma_f32_32x32x16_bf16 v[16:31], v[224:227], v[148:151], v[16:31]
	v_cvt_pk_bf16_f32 v154, v68, v69
	v_add_f32_e32 v250, v95, v250
	v_add_f32_e32 v250, v64, v250
	v_mfma_f32_32x32x16_bf16 v[0:15], v[228:231], v[148:151], v[0:15]
	v_cvt_pk_bf16_f32 v155, v70, v71
	v_add_f32_e32 v250, v65, v250
	v_add_f32_e32 v250, v66, v250
	s_waitcnt lgkmcnt(4)
	v_add_u32_e32 v97, s101, v177
	ds_read_b128 v[200:203], v97
	ds_read_b128 v[204:207], v97 offset:8192
	v_add_u32_e32 v126, s101, v178
	ds_read_b128 v[208:211], v126
	ds_read_b128 v[212:215], v126 offset:8192
	v_add_u32_e32 v97, s101, v179
	ds_read_b128 v[216:219], v97
	ds_read_b128 v[220:223], v97 offset:8192
	v_add_u32_e32 v126, s101, v180
	ds_read_b128 v[224:227], v126
	ds_read_b128 v[228:231], v126 offset:8192
	v_mfma_f32_32x32x16_bf16 v[48:63], v[98:101], v[152:155], v[48:63]
	v_cvt_pk_bf16_f32 v156, v72, v73
	v_add_f32_e32 v250, v67, v250
	v_add_f32_e32 v250, v68, v250
	v_mfma_f32_32x32x16_bf16 v[32:47], v[102:105], v[152:155], v[32:47]
	v_cvt_pk_bf16_f32 v157, v74, v75
	v_add_f32_e32 v250, v69, v250
	v_add_f32_e32 v250, v70, v250
	v_mfma_f32_32x32x16_bf16 v[16:31], v[106:109], v[152:155], v[16:31]
	v_cvt_pk_bf16_f32 v158, v76, v77
	v_add_f32_e32 v250, v71, v250
	v_add_f32_e32 v250, v72, v250
	v_mfma_f32_32x32x16_bf16 v[0:15], v[110:113], v[152:155], v[0:15]
	v_cvt_pk_bf16_f32 v159, v78, v79
	v_add_f32_e32 v250, v73, v250
	v_add_f32_e32 v250, v74, v250
	s_waitcnt lgkmcnt(8)
	v_mfma_f32_32x32x16_bf16 v[48:63], v[114:117], v[156:159], v[48:63]
	v_add_f32_e32 v250, v75, v250
	v_add_f32_e32 v250, v76, v250
	v_mfma_f32_32x32x16_bf16 v[32:47], v[118:121], v[156:159], v[32:47]
	v_add_f32_e32 v250, v77, v250
	v_add_f32_e32 v250, v78, v250
	v_mfma_f32_32x32x16_bf16 v[16:31], v[122:125], v[156:159], v[16:31]
	v_add_f32_e32 v250, v79, v250
	v_mfma_f32_32x32x16_bf16 v[0:15], v[196:199], v[156:159], v[0:15]
	v_add_f32_e32 v181, v181, v250
	s_setprio 0
